# attention output (full-row dwordx4) stores write-through (sc1), on top of v81
# speedup vs baseline: 1.0003x; 1.0001x over previous
; __device__ __forceinline__ unsigned cvt_pk_bf16(float lo, float hi) { const f32x2 v = {lo, hi}; const bf16x2_t b = __builtin_convertvector(v, bf16x2_t); return __builtin_bit_cast(unsigned, b); }
; __device__ __forceinline__ int crow(int r, int hi) { return (r & 3) + 8 * (r >> 2) + 4 * hi; }
; __device__ __forceinline__ void attn_block(const Ptrs& P, int b, int h, int qb, LAS char* lds) {
;     ...
;     if (hi == 0) li_l[r32] = l_reg; asm volatile("s_waitcnt lgkmcnt(0)" ::: "memory");
;     float rli[16];
; #pragma unroll
;     for (int r = 0; r < 16; ++r) rli[r] = __builtin_amdgcn_rcpf(li_l[crow(r, hi)]);
;     const bool odd = (r32 & 1) != 0;
;     bf16* Ow = P.o_() + ((size_t)(b * SEQ + i0 + wid * QBLK + 4 * hi + (odd ? 1 : 0))) * DM + h * DV + (r32 & ~1);
; #pragma unroll
;     for (int r = 0; r < 16; r += 2) { const int rrow = (r & 3) + 8 * (r >> 2);
; #pragma unroll
;         for (int d0 = 0; d0 < 4; ++d0) { const float va = o[d0][r] * rli[r], vb = o[d0][r + 1] * rli[r + 1];
;             const float send = odd ? va : vb;
;             const float recv = __uint_as_float((unsigned)__builtin_amdgcn_update_dpp(0, (int)__float_as_uint(send), 0xB1  , 0xF, 0xF, false));
;             *(unsigned*)(Ow + (size_t)rrow * DM + d0 * 32) = odd ? cvt_pk_bf16(recv, vb) : cvt_pk_bf16(va, recv); } }
.LBB0_611:
	s_or_b64 exec, exec, s[22:23]
	s_waitcnt lgkmcnt(0)
	ds_read_b128 v[68:71], v193
	ds_read_b128 v[72:75], v193 offset:32
	ds_read_b128 v[76:79], v193 offset:64
	ds_read_b128 v[80:83], v193 offset:96
	s_mov_b64 s[22:23], 0
	s_mul_i32 s98, s6, 0x110
	s_mov_b64 s[100:101], 0x4000
	v_and_b32_e32 v86, 0xfff, v192
	v_and_b32_e32 v88, 30, v0
	v_and_b32_e32 v92, 63, v0
	v_or_b32_e32 v84, s74, v192
	v_add_u32_e32 v84, s6, v84
	v_sub_u32_e32 v84, v84, v86
	v_lshrrev_b32_e32 v89, 4, v92
	v_add_u32_e32 v84, v84, v89
	v_ashrrev_i32_e32 v85, 31, v84
	v_lshlrev_b64 v[84:85], 12, v[84:85]
	v_lshl_add_u64 v[90:91], v[172:173], 0, v[84:85]
	v_and_b32_e32 v92, 15, v92
	v_lshlrev_b32_e32 v84, 4, v92
	v_lshlrev_b32_e32 v85, 1, v88
	v_sub_u32_e32 v84, v84, v85
	v_ashrrev_i32_e32 v85, 31, v84
	v_lshl_add_u64 v[90:91], v[90:91], 0, v[84:85]
	v_mul_u32_u24_e32 v86, 0x110, v86
	v_lshl_add_u32 v86, v88, 1, v86
	v_add_u32_e32 v86, s98, v86
	v_mul_u32_u24_e32 v89, 0x110, v89
	v_lshl_add_u32 v89, v92, 4, v89
	v_add_u32_e32 v89, s98, v89
	v_mov_b32_e32 v87, 0x3020706
	v_mov_b32_e32 v88, 0x5040100
	s_nop 0
	v_cndmask_b32_e64 v87, v87, v88, s[4:5]
	s_waitcnt lgkmcnt(0)
	v_rcp_f32_e32 v68, v68
	v_rcp_f32_e32 v69, v69
	v_rcp_f32_e32 v70, v70
	v_rcp_f32_e32 v71, v71
	v_rcp_f32_e32 v72, v72
	v_rcp_f32_e32 v73, v73
	v_rcp_f32_e32 v74, v74
	v_rcp_f32_e32 v75, v75
	v_rcp_f32_e32 v76, v76
	v_rcp_f32_e32 v77, v77
	v_rcp_f32_e32 v78, v78
	v_rcp_f32_e32 v79, v79
	v_rcp_f32_e32 v80, v80
	v_rcp_f32_e32 v81, v81
	v_rcp_f32_e32 v82, v82
	v_rcp_f32_e32 v83, v83
	v_mul_f32_e32 v52, v52, v68
	v_mul_f32_e32 v53, v53, v69
	v_mul_f32_e32 v36, v36, v68
	v_mul_f32_e32 v37, v37, v69
	v_mul_f32_e32 v20, v20, v68
	v_mul_f32_e32 v21, v21, v69
	v_mul_f32_e32 v4, v4, v68
	v_mul_f32_e32 v5, v5, v69
	v_cvt_pk_bf16_f32 v52, v52, v53
	v_cvt_pk_bf16_f32 v36, v36, v37
	v_cvt_pk_bf16_f32 v20, v20, v21
	v_cvt_pk_bf16_f32 v4, v4, v5
	s_nop 0
	v_mov_b32_dpp v53, v52 quad_perm:[1,0,3,2] row_mask:0xf bank_mask:0xf
	v_mov_b32_dpp v37, v36 quad_perm:[1,0,3,2] row_mask:0xf bank_mask:0xf
	v_mov_b32_dpp v21, v20 quad_perm:[1,0,3,2] row_mask:0xf bank_mask:0xf
	v_mov_b32_dpp v5, v4 quad_perm:[1,0,3,2] row_mask:0xf bank_mask:0xf
	v_perm_b32 v52, v53, v52, v87
	v_perm_b32 v36, v37, v36, v87
	v_perm_b32 v20, v21, v20, v87
	v_perm_b32 v4, v5, v4, v87
	ds_write_b32 v86, v52 offset:0
	ds_write_b32 v86, v36 offset:64
	ds_write_b32 v86, v20 offset:128
	ds_write_b32 v86, v4 offset:192
	v_mul_f32_e32 v54, v54, v70
	v_mul_f32_e32 v55, v55, v71
	v_mul_f32_e32 v38, v38, v70
	v_mul_f32_e32 v39, v39, v71
	v_mul_f32_e32 v22, v22, v70
	v_mul_f32_e32 v23, v23, v71
	v_mul_f32_e32 v6, v6, v70
	v_mul_f32_e32 v7, v7, v71
	v_cvt_pk_bf16_f32 v54, v54, v55
	v_cvt_pk_bf16_f32 v38, v38, v39
	v_cvt_pk_bf16_f32 v22, v22, v23
	v_cvt_pk_bf16_f32 v6, v6, v7
	s_nop 0
	v_mov_b32_dpp v55, v54 quad_perm:[1,0,3,2] row_mask:0xf bank_mask:0xf
	v_mov_b32_dpp v39, v38 quad_perm:[1,0,3,2] row_mask:0xf bank_mask:0xf
	v_mov_b32_dpp v23, v22 quad_perm:[1,0,3,2] row_mask:0xf bank_mask:0xf
	v_mov_b32_dpp v7, v6 quad_perm:[1,0,3,2] row_mask:0xf bank_mask:0xf
	v_perm_b32 v54, v55, v54, v87
	v_perm_b32 v38, v39, v38, v87
	v_perm_b32 v22, v23, v22, v87
	v_perm_b32 v6, v7, v6, v87
	ds_write_b32 v86, v54 offset:544
	ds_write_b32 v86, v38 offset:608
	ds_write_b32 v86, v22 offset:672
	ds_write_b32 v86, v6 offset:736
	v_mul_f32_e32 v56, v56, v72
	v_mul_f32_e32 v57, v57, v73
	v_mul_f32_e32 v40, v40, v72
	v_mul_f32_e32 v41, v41, v73
	v_mul_f32_e32 v24, v24, v72
	v_mul_f32_e32 v25, v25, v73
	v_mul_f32_e32 v8, v8, v72
	v_mul_f32_e32 v9, v9, v73
	v_cvt_pk_bf16_f32 v56, v56, v57
	v_cvt_pk_bf16_f32 v40, v40, v41
	v_cvt_pk_bf16_f32 v24, v24, v25
	v_cvt_pk_bf16_f32 v8, v8, v9
	s_nop 0
	v_mov_b32_dpp v57, v56 quad_perm:[1,0,3,2] row_mask:0xf bank_mask:0xf
	v_mov_b32_dpp v41, v40 quad_perm:[1,0,3,2] row_mask:0xf bank_mask:0xf
	v_mov_b32_dpp v25, v24 quad_perm:[1,0,3,2] row_mask:0xf bank_mask:0xf
	v_mov_b32_dpp v9, v8 quad_perm:[1,0,3,2] row_mask:0xf bank_mask:0xf
	v_perm_b32 v56, v57, v56, v87
	v_perm_b32 v40, v41, v40, v87
	v_perm_b32 v24, v25, v24, v87
	v_perm_b32 v8, v9, v8, v87
	ds_write_b32 v86, v56 offset:2176
	ds_write_b32 v86, v40 offset:2240
	ds_write_b32 v86, v24 offset:2304
	ds_write_b32 v86, v8 offset:2368
	v_mul_f32_e32 v58, v58, v74
	v_mul_f32_e32 v59, v59, v75
	v_mul_f32_e32 v42, v42, v74
	v_mul_f32_e32 v43, v43, v75
	v_mul_f32_e32 v26, v26, v74
	v_mul_f32_e32 v27, v27, v75
	v_mul_f32_e32 v10, v10, v74
	v_mul_f32_e32 v11, v11, v75
	v_cvt_pk_bf16_f32 v58, v58, v59
	v_cvt_pk_bf16_f32 v42, v42, v43
	v_cvt_pk_bf16_f32 v26, v26, v27
	v_cvt_pk_bf16_f32 v10, v10, v11
	s_nop 0
	v_mov_b32_dpp v59, v58 quad_perm:[1,0,3,2] row_mask:0xf bank_mask:0xf
	v_mov_b32_dpp v43, v42 quad_perm:[1,0,3,2] row_mask:0xf bank_mask:0xf
	v_mov_b32_dpp v27, v26 quad_perm:[1,0,3,2] row_mask:0xf bank_mask:0xf
	v_mov_b32_dpp v11, v10 quad_perm:[1,0,3,2] row_mask:0xf bank_mask:0xf
	v_perm_b32 v58, v59, v58, v87
	v_perm_b32 v42, v43, v42, v87
	v_perm_b32 v26, v27, v26, v87
	v_perm_b32 v10, v11, v10, v87
	ds_write_b32 v86, v58 offset:2720
	ds_write_b32 v86, v42 offset:2784
	ds_write_b32 v86, v26 offset:2848
	ds_write_b32 v86, v10 offset:2912
; __device__ __forceinline__ unsigned cvt_pk_bf16(float lo, float hi) { const f32x2 v = {lo, hi}; const bf16x2_t b = __builtin_convertvector(v, bf16x2_t); return __builtin_bit_cast(unsigned, b); }
; __device__ __forceinline__ void attn_block(const Ptrs& P, int b, int h, int qb, LAS char* lds) {
;     ...
;     for (int r = 0; r < 16; r += 2) { const int rrow = (r & 3) + 8 * (r >> 2);
; #pragma unroll
;         for (int d0 = 0; d0 < 4; ++d0) { const float va = o[d0][r] * rli[r], vb = o[d0][r + 1] * rli[r + 1];
;             const float send = odd ? va : vb;
;             const float recv = __uint_as_float((unsigned)__builtin_amdgcn_update_dpp(0, (int)__float_as_uint(send), 0xB1  , 0xF, 0xF, false));
;             *(unsigned*)(Ow + (size_t)rrow * DM + d0 * 32) = odd ? cvt_pk_bf16(recv, vb) : cvt_pk_bf16(va, recv); } }
;     __syncthreads();
	v_mul_f32_e32 v60, v60, v76
	v_mul_f32_e32 v61, v61, v77
	v_mul_f32_e32 v44, v44, v76
	v_mul_f32_e32 v45, v45, v77
	v_mul_f32_e32 v28, v28, v76
	v_mul_f32_e32 v29, v29, v77
	v_mul_f32_e32 v12, v12, v76
	v_mul_f32_e32 v13, v13, v77
	v_cvt_pk_bf16_f32 v60, v60, v61
	v_cvt_pk_bf16_f32 v44, v44, v45
	v_cvt_pk_bf16_f32 v28, v28, v29
	v_cvt_pk_bf16_f32 v12, v12, v13
	s_nop 0
	v_mov_b32_dpp v61, v60 quad_perm:[1,0,3,2] row_mask:0xf bank_mask:0xf
	v_mov_b32_dpp v45, v44 quad_perm:[1,0,3,2] row_mask:0xf bank_mask:0xf
	v_mov_b32_dpp v29, v28 quad_perm:[1,0,3,2] row_mask:0xf bank_mask:0xf
	v_mov_b32_dpp v13, v12 quad_perm:[1,0,3,2] row_mask:0xf bank_mask:0xf
	v_perm_b32 v60, v61, v60, v87
	v_perm_b32 v44, v45, v44, v87
	v_perm_b32 v28, v29, v28, v87
	v_perm_b32 v12, v13, v12, v87
	ds_write_b32 v86, v60 offset:4352
	ds_write_b32 v86, v44 offset:4416
	ds_write_b32 v86, v28 offset:4480
	ds_write_b32 v86, v12 offset:4544
	v_mul_f32_e32 v62, v62, v78
	v_mul_f32_e32 v63, v63, v79
	v_mul_f32_e32 v46, v46, v78
	v_mul_f32_e32 v47, v47, v79
	v_mul_f32_e32 v30, v30, v78
	v_mul_f32_e32 v31, v31, v79
	v_mul_f32_e32 v14, v14, v78
	v_mul_f32_e32 v15, v15, v79
	v_cvt_pk_bf16_f32 v62, v62, v63
	v_cvt_pk_bf16_f32 v46, v46, v47
	v_cvt_pk_bf16_f32 v30, v30, v31
	v_cvt_pk_bf16_f32 v14, v14, v15
	s_nop 0
	v_mov_b32_dpp v63, v62 quad_perm:[1,0,3,2] row_mask:0xf bank_mask:0xf
	v_mov_b32_dpp v47, v46 quad_perm:[1,0,3,2] row_mask:0xf bank_mask:0xf
	v_mov_b32_dpp v31, v30 quad_perm:[1,0,3,2] row_mask:0xf bank_mask:0xf
	v_mov_b32_dpp v15, v14 quad_perm:[1,0,3,2] row_mask:0xf bank_mask:0xf
	v_perm_b32 v62, v63, v62, v87
	v_perm_b32 v46, v47, v46, v87
	v_perm_b32 v30, v31, v30, v87
	v_perm_b32 v14, v15, v14, v87
	ds_write_b32 v86, v62 offset:4896
	ds_write_b32 v86, v46 offset:4960
	ds_write_b32 v86, v30 offset:5024
	ds_write_b32 v86, v14 offset:5088
	v_mul_f32_e32 v64, v64, v80
	v_mul_f32_e32 v65, v65, v81
	v_mul_f32_e32 v48, v48, v80
	v_mul_f32_e32 v49, v49, v81
	v_mul_f32_e32 v32, v32, v80
	v_mul_f32_e32 v33, v33, v81
	v_mul_f32_e32 v16, v16, v80
	v_mul_f32_e32 v17, v17, v81
	v_cvt_pk_bf16_f32 v64, v64, v65
	v_cvt_pk_bf16_f32 v48, v48, v49
	v_cvt_pk_bf16_f32 v32, v32, v33
	v_cvt_pk_bf16_f32 v16, v16, v17
	s_nop 0
	v_mov_b32_dpp v65, v64 quad_perm:[1,0,3,2] row_mask:0xf bank_mask:0xf
	v_mov_b32_dpp v49, v48 quad_perm:[1,0,3,2] row_mask:0xf bank_mask:0xf
	v_mov_b32_dpp v33, v32 quad_perm:[1,0,3,2] row_mask:0xf bank_mask:0xf
	v_mov_b32_dpp v17, v16 quad_perm:[1,0,3,2] row_mask:0xf bank_mask:0xf
	v_perm_b32 v64, v65, v64, v87
	v_perm_b32 v48, v49, v48, v87
	v_perm_b32 v32, v33, v32, v87
	v_perm_b32 v16, v17, v16, v87
	ds_write_b32 v86, v64 offset:6528
	ds_write_b32 v86, v48 offset:6592
	ds_write_b32 v86, v32 offset:6656
	ds_write_b32 v86, v16 offset:6720
	v_mul_f32_e32 v66, v66, v82
	v_mul_f32_e32 v67, v67, v83
	v_mul_f32_e32 v50, v50, v82
	v_mul_f32_e32 v51, v51, v83
	v_mul_f32_e32 v34, v34, v82
	v_mul_f32_e32 v35, v35, v83
	v_mul_f32_e32 v18, v18, v82
	v_mul_f32_e32 v19, v19, v83
	v_cvt_pk_bf16_f32 v66, v66, v67
	v_cvt_pk_bf16_f32 v50, v50, v51
	v_cvt_pk_bf16_f32 v34, v34, v35
	v_cvt_pk_bf16_f32 v18, v18, v19
	s_nop 0
	v_mov_b32_dpp v67, v66 quad_perm:[1,0,3,2] row_mask:0xf bank_mask:0xf
	v_mov_b32_dpp v51, v50 quad_perm:[1,0,3,2] row_mask:0xf bank_mask:0xf
	v_mov_b32_dpp v35, v34 quad_perm:[1,0,3,2] row_mask:0xf bank_mask:0xf
	v_mov_b32_dpp v19, v18 quad_perm:[1,0,3,2] row_mask:0xf bank_mask:0xf
	v_perm_b32 v66, v67, v66, v87
	v_perm_b32 v50, v51, v50, v87
	v_perm_b32 v34, v35, v34, v87
	v_perm_b32 v18, v19, v18, v87
	ds_write_b32 v86, v66 offset:7072
	ds_write_b32 v86, v50 offset:7136
	ds_write_b32 v86, v34 offset:7200
	ds_write_b32 v86, v18 offset:7264
	s_waitcnt lgkmcnt(0)
	ds_read_b128 v[200:203], v89 offset:0
	ds_read_b128 v[204:207], v89 offset:1088
	ds_read_b128 v[208:211], v89 offset:2176
	ds_read_b128 v[212:215], v89 offset:3264
	s_waitcnt lgkmcnt(3)
	global_store_dwordx4 v[90:91], v[200:203], off sc1
	s_nop 1
	v_lshl_add_u64 v[90:91], v[90:91], 0, s[100:101]
	s_waitcnt lgkmcnt(2)
	global_store_dwordx4 v[90:91], v[204:207], off sc1
	s_nop 1
	v_lshl_add_u64 v[90:91], v[90:91], 0, s[100:101]
	s_waitcnt lgkmcnt(1)
	global_store_dwordx4 v[90:91], v[208:211], off sc1
	s_nop 1
	v_lshl_add_u64 v[90:91], v[90:91], 0, s[100:101]
	s_waitcnt lgkmcnt(0)
	global_store_dwordx4 v[90:91], v[212:215], off sc1
	s_nop 1
	v_lshl_add_u64 v[90:91], v[90:91], 0, s[100:101]
	ds_read_b128 v[200:203], v89 offset:4352
	ds_read_b128 v[204:207], v89 offset:5440
	ds_read_b128 v[208:211], v89 offset:6528
	ds_read_b128 v[212:215], v89 offset:7616
	s_waitcnt lgkmcnt(3)
	global_store_dwordx4 v[90:91], v[200:203], off sc1
	s_nop 1
	v_lshl_add_u64 v[90:91], v[90:91], 0, s[100:101]
	s_waitcnt lgkmcnt(2)
	global_store_dwordx4 v[90:91], v[204:207], off sc1
	s_nop 1
	v_lshl_add_u64 v[90:91], v[90:91], 0, s[100:101]
	s_waitcnt lgkmcnt(1)
	global_store_dwordx4 v[90:91], v[208:211], off sc1
	s_nop 1
	v_lshl_add_u64 v[90:91], v[90:91], 0, s[100:101]
	s_waitcnt lgkmcnt(0)
	global_store_dwordx4 v[90:91], v[212:215], off sc1
	s_nop 1
	v_lshl_add_u64 v[90:91], v[90:91], 0, s[100:101]
	s_and_b64 vcc, exec, s[36:37]
	s_barrier
	s_cbranch_vccnz .LBB0_609
